# grid barrier: non-leader workgroups poll the cross-XCD release generation directly (skip the XCD-local re-publish hop)
# baseline (speedup 1.0000x reference)
.LBB0_281:
	s_or_b64 exec, exec, s[4:5]
	v_cvt_f32_u32_e32 v5, v3
	s_waitcnt vmcnt(0)
	v_readfirstlane_b32 s0, v4
	v_sub_u32_e32 v4, 0, v3
	v_rcp_iflag_f32_e32 v5, v5
	v_add_u32_e32 v6, s0, v0
	v_mul_f32_e32 v5, 0x4f7ffffe, v5
	v_cvt_u32_f32_e32 v5, v5
	v_mul_lo_u32 v0, v4, v5
	v_mul_hi_u32 v0, v5, v0
	v_add_u32_e32 v0, v5, v0
	v_mul_hi_u32 v0, v6, v0
	v_mul_lo_u32 v4, v0, v3
	v_sub_u32_e32 v4, v6, v4
	v_add_u32_e32 v5, 1, v0
	v_cmp_ge_u32_e32 vcc, v4, v3
	s_nop 1
	v_cndmask_b32_e32 v0, v0, v5, vcc
	v_sub_u32_e32 v5, v4, v3
	v_cndmask_b32_e32 v4, v4, v5, vcc
	v_add_u32_e32 v5, 1, v0
	v_cmp_ge_u32_e32 vcc, v4, v3
	v_add_u32_e32 v4, 1, v6
	s_nop 0
	v_cndmask_b32_e32 v0, v0, v5, vcc
	v_mul_lo_u32 v5, v3, v0
	v_add_u32_e32 v3, v5, v3
	v_cmp_ne_u32_e32 vcc, v4, v3
	s_and_saveexec_b64 s[0:1], vcc
	s_xor_b64 s[4:5], exec, s[0:1]
	s_cbranch_execz .LBB0_295
	v_readlane_b32 s0, v255, 13
	v_readlane_b32 s1, v255, 14
	s_waitcnt lgkmcnt(0)
	s_nop 3
	global_load_dword v2, v1, s[0:1] sc1
	s_waitcnt vmcnt(0)
	v_cmp_eq_u32_e32 vcc, v2, v0
	s_and_saveexec_b64 s[6:7], vcc
	s_cbranch_execz .LBB0_294
	s_mov_b32 s0, 1
	s_mov_b64 s[8:9], 0
	s_branch .LBB0_285

.LBB0_1422:
	s_or_b64 exec, exec, s[4:5]
	v_cvt_f32_u32_e32 v5, v3
	s_waitcnt vmcnt(0)
	v_readfirstlane_b32 s0, v4
	v_sub_u32_e32 v4, 0, v3
	v_rcp_iflag_f32_e32 v5, v5
	v_add_u32_e32 v6, s0, v0
	v_mul_f32_e32 v5, 0x4f7ffffe, v5
	v_cvt_u32_f32_e32 v5, v5
	v_mul_lo_u32 v0, v4, v5
	v_mul_hi_u32 v0, v5, v0
	v_add_u32_e32 v0, v5, v0
	v_mul_hi_u32 v0, v6, v0
	v_mul_lo_u32 v4, v0, v3
	v_sub_u32_e32 v4, v6, v4
	v_add_u32_e32 v5, 1, v0
	v_cmp_ge_u32_e32 vcc, v4, v3
	s_nop 1
	v_cndmask_b32_e32 v0, v0, v5, vcc
	v_sub_u32_e32 v5, v4, v3
	v_cndmask_b32_e32 v4, v4, v5, vcc
	v_add_u32_e32 v5, 1, v0
	v_cmp_ge_u32_e32 vcc, v4, v3
	v_add_u32_e32 v4, 1, v6
	s_nop 0
	v_cndmask_b32_e32 v0, v0, v5, vcc
	v_mul_lo_u32 v5, v3, v0
	v_add_u32_e32 v3, v5, v3
	v_cmp_ne_u32_e32 vcc, v4, v3
	s_and_saveexec_b64 s[0:1], vcc
	s_xor_b64 s[4:5], exec, s[0:1]
	s_cbranch_execz .LBB0_1436
	v_readlane_b32 s0, v255, 13
	v_readlane_b32 s1, v255, 14
	s_waitcnt lgkmcnt(0)
	s_nop 3
	global_load_dword v2, v1, s[0:1] sc1
	s_waitcnt vmcnt(0)
	v_cmp_eq_u32_e32 vcc, v2, v0
	s_and_saveexec_b64 s[6:7], vcc
	s_cbranch_execz .LBB0_1435
	s_mov_b32 s0, 1
	s_mov_b64 s[10:11], 0
	s_branch .LBB0_1426
